# stack30 + seam 5 (P5->P7) replaced by a dataflow handshake: y stores written through, per-row-panel counter, the 8 column-tile owners of a panel wait only for each other
# speedup vs baseline: 1.0089x; 1.0010x over previous
.LBB0_783:
	s_cmp_gt_i32 s6, 31
	s_cselect_b64 s[24:25], -1, 0
	s_lshl_b32 s7, s6, 8
	s_and_b32 s15, s7, 0x1f00
	s_lshl_b32 s7, s22, 8
	s_and_b32 s17, s7, 0x700
	s_cmp_lt_i32 s6, 32
	s_cselect_b64 s[6:7], -1, 0
	s_and_b64 vcc, s[6:7], exec
	s_cselect_b32 s6, 0, 0x2000000
	v_or_b32_e32 v2, s17, v198
	s_add_u32 s6, s37, s6
	v_add_u32_e32 v4, s15, v196
	s_addc_u32 s7, s38, 0
	v_lshlrev_b32_e32 v2, 1, v2
	v_mov_b32_e32 v5, v3
	v_lshl_add_u64 v[186:187], s[6:7], 0, v[2:3]
	v_lshlrev_b64 v[194:195], 12, v[4:5]
	v_lshl_add_u64 v[66:67], v[186:187], 0, v[194:195]
	global_load_dwordx4 v[62:65], v[66:67], off nt
	global_load_dwordx4 v[90:93], v[66:67], off offset:256 nt
	v_or_b32_e32 v66, 16, v4
	v_mov_b32_e32 v67, v3
	v_lshlrev_b64 v[192:193], 12, v[66:67]
	v_lshl_add_u64 v[66:67], v[186:187], 0, v[192:193]
	global_load_dwordx4 v[86:89], v[66:67], off nt
	global_load_dwordx4 v[122:125], v[66:67], off offset:256 nt
	v_or_b32_e32 v66, 32, v4
	v_mov_b32_e32 v67, v3
	v_lshlrev_b64 v[190:191], 12, v[66:67]
	v_lshl_add_u64 v[66:67], v[186:187], 0, v[190:191]
	global_load_dwordx4 v[118:121], v[66:67], off nt
	global_load_dwordx4 v[146:149], v[66:67], off offset:256 nt
	v_or_b32_e32 v66, 48, v4
	v_mov_b32_e32 v67, v3
	v_lshlrev_b64 v[188:189], 12, v[66:67]
	v_lshl_add_u64 v[66:67], v[186:187], 0, v[188:189]
	global_load_dwordx4 v[142:145], v[66:67], off nt
	global_load_dwordx4 v[166:169], v[66:67], off offset:256 nt
	s_waitcnt vmcnt(0)
	v_lshlrev_b32_e32 v66, 16, v62
	v_and_b32_e32 v67, 0xffff0000, v62
	v_lshlrev_b32_e32 v62, 16, v63
	v_and_b32_e32 v63, 0xffff0000, v63
	v_lshlrev_b32_e32 v200, 16, v64
	v_and_b32_e32 v201, 0xffff0000, v64
	v_lshlrev_b32_e32 v68, 16, v65
	v_and_b32_e32 v69, 0xffff0000, v65
	v_pk_mul_f32 v[64:65], v[84:85], v[62:63]
	v_pk_mul_f32 v[62:63], v[82:83], v[66:67]
	v_pk_mul_f32 v[68:69], v[80:81], v[68:69]
	v_pk_mul_f32 v[66:67], v[78:79], v[200:201]
	s_cbranch_vccnz .LBB0_785
	v_cvt_pk_bf16_f32 v62, v62, v63
	v_cvt_pk_bf16_f32 v63, v64, v65
	v_cvt_pk_bf16_f32 v64, v66, v67
	v_lshl_add_u64 v[66:67], s[8:9], 0, v[194:195]
	v_cvt_pk_bf16_f32 v65, v68, v69
	v_lshl_add_u64 v[66:67], v[66:67], 0, v[2:3]
	global_store_dwordx4 v[66:67], v[62:65], off sc1
	v_mov_b64_e32 v[66:67], v[78:79]
	v_mov_b64_e32 v[68:69], v[80:81]
	v_mov_b64_e32 v[62:63], v[82:83]
	v_mov_b64_e32 v[64:65], v[84:85]
.LBB0_785:
	v_lshlrev_b32_e32 v78, 16, v90
	v_and_b32_e32 v79, 0xffff0000, v90
	v_lshlrev_b32_e32 v80, 16, v91
	v_and_b32_e32 v81, 0xffff0000, v91
	v_lshlrev_b32_e32 v82, 16, v92
	v_and_b32_e32 v83, 0xffff0000, v92
	v_lshlrev_b32_e32 v84, 16, v93
	v_and_b32_e32 v85, 0xffff0000, v93
	v_cndmask_b32_e64 v5, 0, 1, s[24:25]
	v_pk_mul_f32 v[80:81], v[164:165], v[80:81]
	v_pk_mul_f32 v[78:79], v[162:163], v[78:79]
	v_pk_mul_f32 v[84:85], v[160:161], v[84:85]
	v_cmp_ne_u32_e64 s[6:7], 1, v5
	s_andn2_b64 vcc, exec, s[24:25]
	v_pk_mul_f32 v[82:83], v[158:159], v[82:83]
	s_cbranch_vccnz .LBB0_787
	v_cvt_pk_bf16_f32 v78, v78, v79
	v_cvt_pk_bf16_f32 v79, v80, v81
	v_cvt_pk_bf16_f32 v80, v82, v83
	v_lshl_add_u64 v[82:83], s[8:9], 0, v[194:195]
	v_cvt_pk_bf16_f32 v81, v84, v85
	v_lshl_add_u64 v[82:83], v[82:83], 0, v[2:3]
	global_store_dwordx4 v[82:83], v[78:81], off offset:256 sc1
	v_mov_b64_e32 v[82:83], v[158:159]
	v_mov_b64_e32 v[84:85], v[160:161]
	v_mov_b64_e32 v[78:79], v[162:163]
	v_mov_b64_e32 v[80:81], v[164:165]
.LBB0_787:
	v_lshlrev_b32_e32 v90, 16, v86
	v_and_b32_e32 v91, 0xffff0000, v86
	v_lshlrev_b32_e32 v86, 16, v87
	v_and_b32_e32 v87, 0xffff0000, v87
	v_lshlrev_b32_e32 v158, 16, v88
	v_and_b32_e32 v159, 0xffff0000, v88
	v_lshlrev_b32_e32 v92, 16, v89
	v_and_b32_e32 v93, 0xffff0000, v89
	v_pk_mul_f32 v[88:89], v[108:109], v[86:87]
	v_pk_mul_f32 v[86:87], v[106:107], v[90:91]
	v_pk_mul_f32 v[92:93], v[104:105], v[92:93]
	s_and_b64 vcc, exec, s[6:7]
	v_pk_mul_f32 v[90:91], v[102:103], v[158:159]
	s_cbranch_vccnz .LBB0_789
	v_cvt_pk_bf16_f32 v86, v86, v87
	v_cvt_pk_bf16_f32 v87, v88, v89
	v_cvt_pk_bf16_f32 v88, v90, v91
	v_lshl_add_u64 v[90:91], s[8:9], 0, v[192:193]
	v_cvt_pk_bf16_f32 v89, v92, v93
	v_lshl_add_u64 v[90:91], v[90:91], 0, v[2:3]
	global_store_dwordx4 v[90:91], v[86:89], off sc1
	v_mov_b64_e32 v[90:91], v[102:103]
	v_mov_b64_e32 v[92:93], v[104:105]
	v_mov_b64_e32 v[86:87], v[106:107]
	v_mov_b64_e32 v[88:89], v[108:109]
.LBB0_789:
	v_lshlrev_b32_e32 v102, 16, v122
	v_and_b32_e32 v103, 0xffff0000, v122
	v_lshlrev_b32_e32 v104, 16, v123
	v_and_b32_e32 v105, 0xffff0000, v123
	v_lshlrev_b32_e32 v106, 16, v124
	v_and_b32_e32 v107, 0xffff0000, v124
	v_lshlrev_b32_e32 v108, 16, v125
	v_and_b32_e32 v109, 0xffff0000, v125
	v_pk_mul_f32 v[104:105], v[156:157], v[104:105]
	v_pk_mul_f32 v[102:103], v[154:155], v[102:103]
	v_pk_mul_f32 v[108:109], v[152:153], v[108:109]
	s_and_b64 vcc, exec, s[6:7]
	v_pk_mul_f32 v[106:107], v[150:151], v[106:107]
	s_cbranch_vccnz .LBB0_791
	v_cvt_pk_bf16_f32 v102, v102, v103
	v_cvt_pk_bf16_f32 v103, v104, v105
	v_cvt_pk_bf16_f32 v104, v106, v107
	v_lshl_add_u64 v[106:107], s[8:9], 0, v[192:193]
	v_cvt_pk_bf16_f32 v105, v108, v109
	v_lshl_add_u64 v[106:107], v[106:107], 0, v[2:3]
	global_store_dwordx4 v[106:107], v[102:105], off offset:256 sc1
	v_mov_b64_e32 v[106:107], v[150:151]
	v_mov_b64_e32 v[108:109], v[152:153]
	v_mov_b64_e32 v[102:103], v[154:155]
	v_mov_b64_e32 v[104:105], v[156:157]
.LBB0_791:
	v_lshlrev_b32_e32 v122, 16, v118
	v_and_b32_e32 v123, 0xffff0000, v118
	v_lshlrev_b32_e32 v118, 16, v119
	v_and_b32_e32 v119, 0xffff0000, v119
	v_lshlrev_b32_e32 v150, 16, v120
	v_and_b32_e32 v151, 0xffff0000, v120
	v_lshlrev_b32_e32 v124, 16, v121
	v_and_b32_e32 v125, 0xffff0000, v121
	v_pk_mul_f32 v[120:121], v[140:141], v[118:119]
	v_pk_mul_f32 v[118:119], v[138:139], v[122:123]
	v_pk_mul_f32 v[124:125], v[136:137], v[124:125]
	s_and_b64 vcc, exec, s[6:7]
	v_pk_mul_f32 v[122:123], v[134:135], v[150:151]
	s_cbranch_vccnz .LBB0_793
	v_cvt_pk_bf16_f32 v118, v118, v119
	v_cvt_pk_bf16_f32 v119, v120, v121
	v_cvt_pk_bf16_f32 v120, v122, v123
	v_lshl_add_u64 v[122:123], s[8:9], 0, v[190:191]
	v_cvt_pk_bf16_f32 v121, v124, v125
	v_lshl_add_u64 v[122:123], v[122:123], 0, v[2:3]
	global_store_dwordx4 v[122:123], v[118:121], off sc1
	v_mov_b64_e32 v[122:123], v[134:135]
	v_mov_b64_e32 v[124:125], v[136:137]
	v_mov_b64_e32 v[118:119], v[138:139]
	v_mov_b64_e32 v[120:121], v[140:141]
.LBB0_793:
	v_lshlrev_b32_e32 v134, 16, v146
	v_and_b32_e32 v135, 0xffff0000, v146
	v_lshlrev_b32_e32 v136, 16, v147
	v_and_b32_e32 v137, 0xffff0000, v147
	v_lshlrev_b32_e32 v138, 16, v148
	v_and_b32_e32 v139, 0xffff0000, v148
	v_lshlrev_b32_e32 v140, 16, v149
	v_and_b32_e32 v141, 0xffff0000, v149
	v_pk_mul_f32 v[136:137], v[132:133], v[136:137]
	v_pk_mul_f32 v[134:135], v[130:131], v[134:135]
	v_pk_mul_f32 v[140:141], v[128:129], v[140:141]
	s_and_b64 vcc, exec, s[6:7]
	v_pk_mul_f32 v[138:139], v[126:127], v[138:139]
	s_cbranch_vccnz .LBB0_795
	v_cvt_pk_bf16_f32 v134, v134, v135
	v_cvt_pk_bf16_f32 v135, v136, v137
	v_cvt_pk_bf16_f32 v136, v138, v139
	v_lshl_add_u64 v[138:139], s[8:9], 0, v[190:191]
	v_cvt_pk_bf16_f32 v137, v140, v141
	v_lshl_add_u64 v[138:139], v[138:139], 0, v[2:3]
	global_store_dwordx4 v[138:139], v[134:137], off offset:256 sc1
	v_mov_b64_e32 v[140:141], v[128:129]
	v_mov_b64_e32 v[138:139], v[126:127]
	v_mov_b64_e32 v[136:137], v[132:133]
	v_mov_b64_e32 v[134:135], v[130:131]
.LBB0_795:
	v_lshlrev_b32_e32 v126, 16, v142
	v_and_b32_e32 v127, 0xffff0000, v142
	v_lshlrev_b32_e32 v128, 16, v143
	v_and_b32_e32 v129, 0xffff0000, v143
	v_lshlrev_b32_e32 v130, 16, v144
	v_and_b32_e32 v131, 0xffff0000, v144
	v_lshlrev_b32_e32 v132, 16, v145
	v_and_b32_e32 v133, 0xffff0000, v145
	v_pk_mul_f32 v[144:145], v[116:117], v[128:129]
	v_pk_mul_f32 v[142:143], v[114:115], v[126:127]
	v_pk_mul_f32 v[148:149], v[112:113], v[132:133]
	s_and_b64 vcc, exec, s[6:7]
	v_pk_mul_f32 v[146:147], v[110:111], v[130:131]
	s_cbranch_vccnz .LBB0_797
	v_cvt_pk_bf16_f32 v126, v142, v143
	v_cvt_pk_bf16_f32 v127, v144, v145
	v_cvt_pk_bf16_f32 v128, v146, v147
	v_cvt_pk_bf16_f32 v129, v148, v149
	v_lshl_add_u64 v[130:131], s[8:9], 0, v[188:189]
	v_mov_b64_e32 v[148:149], v[112:113]
	v_mov_b64_e32 v[144:145], v[116:117]
	v_lshl_add_u64 v[130:131], v[130:131], 0, v[2:3]
	v_mov_b64_e32 v[146:147], v[110:111]
	v_mov_b64_e32 v[142:143], v[114:115]
	global_store_dwordx4 v[130:131], v[126:129], off sc1
.LBB0_797:
	v_lshlrev_b32_e32 v110, 16, v166
	v_and_b32_e32 v111, 0xffff0000, v166
	v_lshlrev_b32_e32 v112, 16, v167
	v_and_b32_e32 v113, 0xffff0000, v167
	v_lshlrev_b32_e32 v114, 16, v168
	v_and_b32_e32 v115, 0xffff0000, v168
	v_lshlrev_b32_e32 v116, 16, v169
	v_and_b32_e32 v117, 0xffff0000, v169
	v_pk_mul_f32 v[112:113], v[100:101], v[112:113]
	v_pk_mul_f32 v[110:111], v[98:99], v[110:111]
	v_pk_mul_f32 v[116:117], v[96:97], v[116:117]
	s_and_b64 vcc, exec, s[6:7]
	v_pk_mul_f32 v[114:115], v[94:95], v[114:115]
	s_cbranch_vccnz .LBB0_799
	v_cvt_pk_bf16_f32 v110, v110, v111
	v_cvt_pk_bf16_f32 v111, v112, v113
	v_cvt_pk_bf16_f32 v112, v114, v115
	v_lshl_add_u64 v[114:115], s[8:9], 0, v[188:189]
	v_cvt_pk_bf16_f32 v113, v116, v117
	v_lshl_add_u64 v[114:115], v[114:115], 0, v[2:3]
	global_store_dwordx4 v[114:115], v[110:113], off offset:256 sc1
	v_mov_b64_e32 v[116:117], v[96:97]
	v_mov_b64_e32 v[114:115], v[94:95]
	v_mov_b64_e32 v[112:113], v[100:101]
	v_mov_b64_e32 v[110:111], v[98:99]
.LBB0_799:
	v_add_u32_e32 v94, 0x80, v4
	v_mov_b32_e32 v95, v3
	v_lshlrev_b64 v[192:193], 12, v[94:95]
	v_lshl_add_u64 v[98:99], v[186:187], 0, v[192:193]
	global_load_dwordx4 v[94:97], v[98:99], off nt
	global_load_dwordx4 v[130:133], v[98:99], off offset:256 nt
	v_add_u32_e32 v98, 0x90, v4
	v_mov_b32_e32 v99, v3
	v_lshlrev_b64 v[190:191], 12, v[98:99]
	v_lshl_add_u64 v[98:99], v[186:187], 0, v[190:191]
	global_load_dwordx4 v[126:129], v[98:99], off nt
	global_load_dwordx4 v[158:161], v[98:99], off offset:256 nt
	v_add_u32_e32 v98, 0xa0, v4
	v_mov_b32_e32 v99, v3
	v_lshlrev_b64 v[188:189], 12, v[98:99]
	v_add_u32_e32 v4, 0xb0, v4
	v_mov_b32_e32 v5, v3
	v_lshl_add_u64 v[98:99], v[186:187], 0, v[188:189]
	v_lshlrev_b64 v[4:5], 12, v[4:5]
	global_load_dwordx4 v[150:153], v[98:99], off nt
	global_load_dwordx4 v[166:169], v[98:99], off offset:256 nt
	v_lshl_add_u64 v[98:99], v[186:187], 0, v[4:5]
	global_load_dwordx4 v[162:165], v[98:99], off nt
	global_load_dwordx4 v[154:157], v[98:99], off offset:256 nt
	s_and_b64 vcc, exec, s[6:7]
	s_waitcnt vmcnt(7)
	v_lshlrev_b32_e32 v98, 16, v94
	v_and_b32_e32 v99, 0xffff0000, v94
	v_lshlrev_b32_e32 v94, 16, v95
	v_and_b32_e32 v95, 0xffff0000, v95
	v_lshlrev_b32_e32 v186, 16, v96
	v_and_b32_e32 v187, 0xffff0000, v96
	v_lshlrev_b32_e32 v96, 16, v97
	v_and_b32_e32 v97, 0xffff0000, v97
	v_pk_mul_f32 v[100:101], v[76:77], v[94:95]
	v_pk_mul_f32 v[98:99], v[74:75], v[98:99]
	v_pk_mul_f32 v[96:97], v[72:73], v[96:97]
	v_pk_mul_f32 v[94:95], v[70:71], v[186:187]
	s_cbranch_vccnz .LBB0_801
	v_cvt_pk_bf16_f32 v98, v98, v99
	v_cvt_pk_bf16_f32 v99, v100, v101
	v_cvt_pk_bf16_f32 v100, v94, v95
	v_lshl_add_u64 v[94:95], s[8:9], 0, v[192:193]
	v_cvt_pk_bf16_f32 v101, v96, v97
	v_lshl_add_u64 v[94:95], v[94:95], 0, v[2:3]
	global_store_dwordx4 v[94:95], v[98:101], off sc1
	v_mov_b64_e32 v[96:97], v[72:73]
	v_mov_b64_e32 v[94:95], v[70:71]
	v_mov_b64_e32 v[100:101], v[76:77]
	v_mov_b64_e32 v[98:99], v[74:75]
.LBB0_801:
	s_waitcnt vmcnt(6)
	v_lshlrev_b32_e32 v70, 16, v130
	v_and_b32_e32 v71, 0xffff0000, v130
	v_lshlrev_b32_e32 v72, 16, v131
	v_and_b32_e32 v73, 0xffff0000, v131
	v_lshlrev_b32_e32 v74, 16, v132
	v_and_b32_e32 v75, 0xffff0000, v132
	v_lshlrev_b32_e32 v76, 16, v133
	v_and_b32_e32 v77, 0xffff0000, v133
	v_pk_mul_f32 v[72:73], v[60:61], v[72:73]
	v_pk_mul_f32 v[70:71], v[58:59], v[70:71]
	v_pk_mul_f32 v[76:77], v[56:57], v[76:77]
	s_and_b64 vcc, exec, s[6:7]
	v_pk_mul_f32 v[74:75], v[54:55], v[74:75]
	s_cbranch_vccnz .LBB0_803
	v_cvt_pk_bf16_f32 v70, v70, v71
	v_cvt_pk_bf16_f32 v71, v72, v73
	v_cvt_pk_bf16_f32 v72, v74, v75
	v_lshl_add_u64 v[74:75], s[8:9], 0, v[192:193]
	v_cvt_pk_bf16_f32 v73, v76, v77
	v_lshl_add_u64 v[74:75], v[74:75], 0, v[2:3]
	global_store_dwordx4 v[74:75], v[70:73], off offset:256 sc1
	v_mov_b64_e32 v[76:77], v[56:57]
	v_mov_b64_e32 v[74:75], v[54:55]
	v_mov_b64_e32 v[72:73], v[60:61]
	v_mov_b64_e32 v[70:71], v[58:59]
.LBB0_803:
	s_waitcnt vmcnt(5)
	v_lshlrev_b32_e32 v54, 16, v126
	v_and_b32_e32 v55, 0xffff0000, v126
	v_lshlrev_b32_e32 v56, 16, v127
	v_and_b32_e32 v57, 0xffff0000, v127
	v_lshlrev_b32_e32 v58, 16, v128
	v_and_b32_e32 v59, 0xffff0000, v128
	v_lshlrev_b32_e32 v60, 16, v129
	v_and_b32_e32 v61, 0xffff0000, v129
	v_pk_mul_f32 v[128:129], v[52:53], v[56:57]
	v_pk_mul_f32 v[126:127], v[50:51], v[54:55]
	v_pk_mul_f32 v[132:133], v[48:49], v[60:61]
	s_and_b64 vcc, exec, s[6:7]
	v_pk_mul_f32 v[130:131], v[46:47], v[58:59]
	s_cbranch_vccnz .LBB0_805
	v_cvt_pk_bf16_f32 v54, v126, v127
	v_cvt_pk_bf16_f32 v55, v128, v129
	v_cvt_pk_bf16_f32 v56, v130, v131
	v_cvt_pk_bf16_f32 v57, v132, v133
	v_lshl_add_u64 v[58:59], s[8:9], 0, v[190:191]
	v_mov_b64_e32 v[132:133], v[48:49]
	v_mov_b64_e32 v[128:129], v[52:53]
	v_lshl_add_u64 v[58:59], v[58:59], 0, v[2:3]
	v_mov_b64_e32 v[130:131], v[46:47]
	v_mov_b64_e32 v[126:127], v[50:51]
	global_store_dwordx4 v[58:59], v[54:57], off sc1
.LBB0_805:
	s_waitcnt vmcnt(4)
	v_lshlrev_b32_e32 v46, 16, v158
	v_and_b32_e32 v47, 0xffff0000, v158
	v_lshlrev_b32_e32 v48, 16, v159
	v_and_b32_e32 v49, 0xffff0000, v159
	v_lshlrev_b32_e32 v50, 16, v160
	v_and_b32_e32 v51, 0xffff0000, v160
	v_lshlrev_b32_e32 v52, 16, v161
	v_and_b32_e32 v53, 0xffff0000, v161
	v_pk_mul_f32 v[48:49], v[44:45], v[48:49]
	v_pk_mul_f32 v[46:47], v[42:43], v[46:47]
	v_pk_mul_f32 v[52:53], v[40:41], v[52:53]
	s_and_b64 vcc, exec, s[6:7]
	v_pk_mul_f32 v[50:51], v[38:39], v[50:51]
	s_cbranch_vccnz .LBB0_807
	v_cvt_pk_bf16_f32 v46, v46, v47
	v_cvt_pk_bf16_f32 v47, v48, v49
	v_cvt_pk_bf16_f32 v48, v50, v51
	v_lshl_add_u64 v[50:51], s[8:9], 0, v[190:191]
	v_cvt_pk_bf16_f32 v49, v52, v53
	v_lshl_add_u64 v[50:51], v[50:51], 0, v[2:3]
	global_store_dwordx4 v[50:51], v[46:49], off offset:256 sc1
	v_mov_b64_e32 v[52:53], v[40:41]
	v_mov_b64_e32 v[50:51], v[38:39]
	v_mov_b64_e32 v[48:49], v[44:45]
	v_mov_b64_e32 v[46:47], v[42:43]
.LBB0_807:
	s_waitcnt vmcnt(3)
	v_lshlrev_b32_e32 v38, 16, v150
	v_and_b32_e32 v39, 0xffff0000, v150
	v_lshlrev_b32_e32 v40, 16, v151
	v_and_b32_e32 v41, 0xffff0000, v151
	v_lshlrev_b32_e32 v42, 16, v152
	v_and_b32_e32 v43, 0xffff0000, v152
	v_lshlrev_b32_e32 v44, 16, v153
	v_and_b32_e32 v45, 0xffff0000, v153
	v_pk_mul_f32 v[152:153], v[36:37], v[40:41]
	v_pk_mul_f32 v[150:151], v[34:35], v[38:39]
	v_pk_mul_f32 v[160:161], v[32:33], v[44:45]
	s_and_b64 vcc, exec, s[6:7]
	v_pk_mul_f32 v[158:159], v[30:31], v[42:43]
	s_cbranch_vccnz .LBB0_809
	v_cvt_pk_bf16_f32 v38, v150, v151
	v_cvt_pk_bf16_f32 v39, v152, v153
	v_cvt_pk_bf16_f32 v40, v158, v159
	v_cvt_pk_bf16_f32 v41, v160, v161
	v_lshl_add_u64 v[42:43], s[8:9], 0, v[188:189]
	v_mov_b64_e32 v[160:161], v[32:33]
	v_mov_b64_e32 v[152:153], v[36:37]
	v_lshl_add_u64 v[42:43], v[42:43], 0, v[2:3]
	v_mov_b64_e32 v[158:159], v[30:31]
	v_mov_b64_e32 v[150:151], v[34:35]
	global_store_dwordx4 v[42:43], v[38:41], off sc1
.LBB0_809:
	s_waitcnt vmcnt(2)
	v_lshlrev_b32_e32 v30, 16, v166
	v_and_b32_e32 v31, 0xffff0000, v166
	v_lshlrev_b32_e32 v32, 16, v167
	v_and_b32_e32 v33, 0xffff0000, v167
	v_lshlrev_b32_e32 v34, 16, v168
	v_and_b32_e32 v35, 0xffff0000, v168
	v_lshlrev_b32_e32 v36, 16, v169
	v_and_b32_e32 v37, 0xffff0000, v169
	v_pk_mul_f32 v[32:33], v[28:29], v[32:33]
	v_pk_mul_f32 v[30:31], v[26:27], v[30:31]
	v_pk_mul_f32 v[36:37], v[24:25], v[36:37]
	s_and_b64 vcc, exec, s[6:7]
	v_pk_mul_f32 v[34:35], v[22:23], v[34:35]
	s_cbranch_vccnz .LBB0_811
	v_cvt_pk_bf16_f32 v30, v30, v31
	v_cvt_pk_bf16_f32 v31, v32, v33
	v_cvt_pk_bf16_f32 v32, v34, v35
	v_lshl_add_u64 v[34:35], s[8:9], 0, v[188:189]
	v_cvt_pk_bf16_f32 v33, v36, v37
	v_lshl_add_u64 v[34:35], v[34:35], 0, v[2:3]
	global_store_dwordx4 v[34:35], v[30:33], off offset:256 sc1
	v_mov_b64_e32 v[36:37], v[24:25]
	v_mov_b64_e32 v[34:35], v[22:23]
	v_mov_b64_e32 v[32:33], v[28:29]
	v_mov_b64_e32 v[30:31], v[26:27]
.LBB0_811:
	s_waitcnt vmcnt(1)
	v_lshlrev_b32_e32 v22, 16, v162
	v_and_b32_e32 v23, 0xffff0000, v162
	v_lshlrev_b32_e32 v24, 16, v163
	v_and_b32_e32 v25, 0xffff0000, v163
	v_lshlrev_b32_e32 v26, 16, v164
	v_and_b32_e32 v27, 0xffff0000, v164
	v_lshlrev_b32_e32 v28, 16, v165
	v_and_b32_e32 v29, 0xffff0000, v165
	v_pk_mul_f32 v[164:165], v[20:21], v[24:25]
	v_pk_mul_f32 v[162:163], v[18:19], v[22:23]
	v_pk_mul_f32 v[168:169], v[16:17], v[28:29]
	s_and_b64 vcc, exec, s[6:7]
	v_pk_mul_f32 v[166:167], v[14:15], v[26:27]
	s_cbranch_vccnz .LBB0_813
	v_cvt_pk_bf16_f32 v22, v162, v163
	v_cvt_pk_bf16_f32 v23, v164, v165
	v_cvt_pk_bf16_f32 v24, v166, v167
	v_cvt_pk_bf16_f32 v25, v168, v169
	v_lshl_add_u64 v[26:27], s[8:9], 0, v[4:5]
	v_mov_b64_e32 v[168:169], v[16:17]
	v_mov_b64_e32 v[164:165], v[20:21]
	v_lshl_add_u64 v[26:27], v[26:27], 0, v[2:3]
	v_mov_b64_e32 v[166:167], v[14:15]
	v_mov_b64_e32 v[162:163], v[18:19]
	global_store_dwordx4 v[26:27], v[22:25], off sc1
.LBB0_813:
	s_waitcnt vmcnt(0)
	v_lshlrev_b32_e32 v14, 16, v154
	v_and_b32_e32 v15, 0xffff0000, v154
	v_lshlrev_b32_e32 v16, 16, v155
	v_and_b32_e32 v17, 0xffff0000, v155
	v_lshlrev_b32_e32 v18, 16, v156
	v_and_b32_e32 v19, 0xffff0000, v156
	v_lshlrev_b32_e32 v20, 16, v157
	v_and_b32_e32 v21, 0xffff0000, v157
	v_pk_mul_f32 v[16:17], v[12:13], v[16:17]
	v_pk_mul_f32 v[14:15], v[10:11], v[14:15]
	v_pk_mul_f32 v[20:21], v[8:9], v[20:21]
	s_and_b64 vcc, exec, s[6:7]
	v_pk_mul_f32 v[18:19], v[6:7], v[18:19]
	s_cbranch_vccnz .LBB0_815
	v_lshl_add_u64 v[4:5], s[8:9], 0, v[4:5]
	v_cvt_pk_bf16_f32 v14, v14, v15
	v_cvt_pk_bf16_f32 v15, v16, v17
	v_cvt_pk_bf16_f32 v16, v18, v19
	v_cvt_pk_bf16_f32 v17, v20, v21
	v_lshl_add_u64 v[4:5], v[4:5], 0, v[2:3]
	global_store_dwordx4 v[4:5], v[14:17], off offset:256 sc1
	v_mov_b64_e32 v[20:21], v[8:9]
	v_mov_b64_e32 v[18:19], v[6:7]
	v_mov_b64_e32 v[16:17], v[12:13]
	v_mov_b64_e32 v[14:15], v[10:11]

.LBB0_832:
	s_waitcnt vmcnt(0)
	s_barrier
	s_and_saveexec_b64 s[6:7], s[84:85]
	s_cbranch_execz .LBB0_886
	s_cmp_lg_u32 s79, 0x100
	s_cbranch_scc1 .Ldf5_full
	s_and_b32 s0, s78, 7
	s_lshl_b32 s0, s0, 5
	s_lshr_b32 s1, s78, 3
	s_add_i32 s0, s0, s1
	s_lshr_b32 s1, s0, 6
	s_lshl_b32 s1, s1, 3
	s_and_b32 s98, s0, 7
	s_add_i32 s98, s98, s1
	s_lshl_b32 s98, s98, 8
	s_add_i32 s98, s98, 0xc000
	v_mov_b32_e32 v2, s98
	v_mov_b32_e32 v3, 1
	global_atomic_add v2, v3, s[76:77]
	s_mov_b32 s99, 0
.Ldf5_poll:
	global_load_dword v4, v2, s[76:77] sc1
	s_waitcnt vmcnt(0)
	v_readfirstlane_b32 s0, v4
	s_cmp_ge_u32 s0, 8
	s_cbranch_scc1 .Ldf5_go
	s_sleep 1
	s_add_i32 s99, s99, 1
	s_cmp_lt_u32 s99, 0x100000
	s_cbranch_scc1 .Ldf5_poll

.Ldf5_full:
	s_add_i32 s0, 0, 0x23e20
	s_waitcnt vmcnt(26)
	v_mov_b32_e32 v2, s0
	s_waitcnt vmcnt(0) expcnt(0) lgkmcnt(0)
	ds_read_b32 v4, v2
	s_add_i32 s0, 0, 0x23e24
	v_mov_b32_e32 v2, s0
	ds_read_b32 v2, v2
	s_waitcnt lgkmcnt(1)
	v_cmp_ne_u32_e32 vcc, 0, v4
	s_cbranch_vccnz .LBB0_850
	s_add_u32 s8, s76, 0x1000
	s_load_dwordx2 s[0:1], s[86:87], 0x4
	s_addc_u32 s9, s77, 0
	s_add_u32 s10, s76, 0x1100
	s_addc_u32 s11, s77, 0
	s_add_u32 s12, s76, 0x1200
	s_addc_u32 s13, s77, 0
	s_waitcnt lgkmcnt(0)
	s_mul_i32 s0, s0, s79
	s_add_u32 s14, s76, 0x1300
	s_mul_i32 s0, s0, s1
	s_addc_u32 s15, s77, 0
	s_mov_b32 s1, 1
	v_mov_b32_e32 v18, 0
	s_branch .LBB0_836
